# grid barrier: L1 invalidate issued just before polling (after the arrival and top-level atomics) so it never delays a release
# baseline (speedup 1.0000x reference)
; __global__ void __launch_bounds__(512) mega(Params P) {
;     ...
;   grid.sync();
.Lgbx_arr_0:
	s_lshl_b32 s1, s1, 2
	s_addk_i32 s1, 0x88
	v_mov_b32_e32 v2, s1
	v_readlane_b32 s98, v255, 20
	s_nop 3
	s_lshl_b32 s99, s98, 16
	v_mov_b32_e32 v0, s99
	s_add_i32 s98, s98, 1
	v_writelane_b32 v255, s98, 20
	v_mov_b32_e32 v3, 1
	global_atomic_add v3, v2, v3, s[4:5] sc0
	s_waitcnt vmcnt(0)
	v_readfirstlane_b32 s1, v3
	s_nop 3
	s_cmp_eq_u32 s96, 0
	s_cbranch_scc1 .Lgbx_cn_0
	s_and_b32 s1, s1, 0xffff
	s_add_i32 s0, s6, -1
	s_cmp_lg_u32 s1, s0
	s_cbranch_scc1 .Lgbx_pp_0
	s_sub_i32 s1, 0x10000, s6
	v_mov_b32_e32 v3, s1
	global_atomic_add v3, v2, v3, s[4:5] sc0
	s_waitcnt vmcnt(0)
	s_branch .Lgbx_top_0

; __global__ void __launch_bounds__(512) mega(Params P) {
;     ...
;   grid.sync();
.Lgbx_top_0:
	v_mov_b32_e32 v3, 1
	global_atomic_add v3, v1, v3, s[4:5] sc0
	s_waitcnt vmcnt(0)
	v_and_b32_e32 v3, 0xffff, v3
	s_nop 0
	v_readfirstlane_b32 s1, v3
	s_nop 3
	s_add_i32 s0, s7, -1
	s_cmp_lg_u32 s1, s0
	s_cbranch_scc1 .Lgbx_pp_0
	s_sub_i32 s1, 0x10000, s7
	v_mov_b32_e32 v3, s1
	global_atomic_add v1, v3, s[4:5]
.Lgbx_pp_0:
	buffer_inv sc1
.Lgbx_poll_0:
	global_load_dword v3, v1, s[4:5] sc1
	s_waitcnt vmcnt(0)
	v_and_b32_e32 v3, 0xffff0000, v3
	v_cmp_ne_u32_e32 vcc, v3, v0
	s_cbranch_vccnz .Lgbx_sw_0
	s_sleep 1
	s_branch .Lgbx_poll_0

; __global__ void __launch_bounds__(512) mega(Params P) {
;     ...
;   for (int l = 0; l < 2; ++l) {
;     if (l > 0) { norm_phase(H, P.attn_norm + l * DM, HN); grid.sync(); }
;     { EpiIn e; e.cqkv = CQKV; e.ka = (bf16_t*)(ws + WS_KA); e.qd = (bf16_t*)(ws + WS_QD); e.kd = (bf16_t*)(ws + WS_KD); e.vtd = (bf16_t*)(ws + WS_VTD);
;       e.qs = (bf16_t*)(ws + WS_QS); e.ks = (bf16_t*)(ws + WS_KS); e.vts = (bf16_t*)(ws + WS_VTS); e.rope = rope;
;       if (EN & 2) gemm_phase(HN, DM, (const bf16_t*)(ws + WS_WIN) + (size_t)l * N_IN * 1024, 1024, NREAL, N_IN, 1024, e); }
;     grid.sync();
;     { EpiUp e; e.qa = (bf16_t*)(ws + WS_QA); e.ka = (bf16_t*)(ws + WS_KA); e.vta = (bf16_t*)(ws + WS_VTA); e.rope = rope; e.brow = 0; e.rs_direct = 0.f; e.use_direct = 0;
;       if (EN & 4) up_phase(CQKV, (const bf16_t*)(ws + WS_WQB) + (size_t)l * 768 * 256, (const bf16_t*)(ws + WS_WKVB) + (size_t)l * 768 * 256, e); }
;     grid.sync();
;     attn_phase(P, l);
;     grid.sync();
;     if (l == 0) { EpiResid0 e; e.H = H; e.xsrc = P.x; e.msrc = P.meta; gemm_phase(HN, DM, (const bf16_t*)(ws + WS_WOUT), 1024, NREAL, 1024, 1024, e); }
;     else { EpiResid e; e.H = H; gemm_phase(HN, DM, (const bf16_t*)(ws + WS_WOUT) + (size_t)l * 1024 * 1024, 1024, NREAL, 1024, 1024, e); }
;     grid.sync();
;     norm_phase(H, P.ffn_norm + l * DM, HN);
;     grid.sync();
;     if (EN & 128) { EpiGU e; e.act = (bf16_t*)(ws + WS_ACT); gemm_phase(HN, DM, (const bf16_t*)(ws + WS_WGU) + (size_t)l * N_GU * 1024, 1024, NREAL, N_GU, 1024, e); }
;     grid.sync();
;     if (EN & 256) { EpiResid e; e.H = H; gemm_phase((const bf16_t*)(ws + WS_ACT), DFF, (const bf16_t*)(ws + WS_WDN) + (size_t)l * 1024 * DFF, DFF, NREAL, 1024, DFF, e); }
;     grid.sync();
.Lgbx_top_1:
	v_mov_b32_e32 v3, 1
	global_atomic_add v3, v1, v3, s[4:5] sc0
	s_waitcnt vmcnt(0)
	v_and_b32_e32 v3, 0xffff, v3
	s_nop 0
	v_readfirstlane_b32 s1, v3
	s_nop 3
	s_add_i32 s0, s7, -1
	s_cmp_lg_u32 s1, s0
	s_cbranch_scc1 .Lgbx_pp_1
	s_sub_i32 s1, 0x10000, s7
	v_mov_b32_e32 v3, s1
	global_atomic_add v1, v3, s[4:5]
.Lgbx_pp_1:
	buffer_inv sc1
.Lgbx_poll_1:
	global_load_dword v3, v1, s[4:5] sc1
	s_waitcnt vmcnt(0)
	v_and_b32_e32 v3, 0xffff0000, v3
	v_cmp_ne_u32_e32 vcc, v3, v0
	s_cbranch_vccnz .Lgbx_sw_1
	s_sleep 1
	s_branch .Lgbx_poll_1

; __global__ void __launch_bounds__(512) mega(Params P) {
;     ...
;   for (int l = 0; l < 2; ++l) {
;     if (l > 0) { norm_phase(H, P.attn_norm + l * DM, HN); grid.sync(); }
;     { EpiIn e; e.cqkv = CQKV; e.ka = (bf16_t*)(ws + WS_KA); e.qd = (bf16_t*)(ws + WS_QD); e.kd = (bf16_t*)(ws + WS_KD); e.vtd = (bf16_t*)(ws + WS_VTD);
;       e.qs = (bf16_t*)(ws + WS_QS); e.ks = (bf16_t*)(ws + WS_KS); e.vts = (bf16_t*)(ws + WS_VTS); e.rope = rope;
;       if (EN & 2) gemm_phase(HN, DM, (const bf16_t*)(ws + WS_WIN) + (size_t)l * N_IN * 1024, 1024, NREAL, N_IN, 1024, e); }
;     grid.sync();
;     { EpiUp e; e.qa = (bf16_t*)(ws + WS_QA); e.ka = (bf16_t*)(ws + WS_KA); e.vta = (bf16_t*)(ws + WS_VTA); e.rope = rope; e.brow = 0; e.rs_direct = 0.f; e.use_direct = 0;
;       if (EN & 4) up_phase(CQKV, (const bf16_t*)(ws + WS_WQB) + (size_t)l * 768 * 256, (const bf16_t*)(ws + WS_WKVB) + (size_t)l * 768 * 256, e); }
;     grid.sync();
;     attn_phase(P, l);
;     grid.sync();
;     if (l == 0) { EpiResid0 e; e.H = H; e.xsrc = P.x; e.msrc = P.meta; gemm_phase(HN, DM, (const bf16_t*)(ws + WS_WOUT), 1024, NREAL, 1024, 1024, e); }
;     else { EpiResid e; e.H = H; gemm_phase(HN, DM, (const bf16_t*)(ws + WS_WOUT) + (size_t)l * 1024 * 1024, 1024, NREAL, 1024, 1024, e); }
;     grid.sync();
;     norm_phase(H, P.ffn_norm + l * DM, HN);
;     grid.sync();
;     if (EN & 128) { EpiGU e; e.act = (bf16_t*)(ws + WS_ACT); gemm_phase(HN, DM, (const bf16_t*)(ws + WS_WGU) + (size_t)l * N_GU * 1024, 1024, NREAL, N_GU, 1024, e); }
;     grid.sync();
;     if (EN & 256) { EpiResid e; e.H = H; gemm_phase((const bf16_t*)(ws + WS_ACT), DFF, (const bf16_t*)(ws + WS_WDN) + (size_t)l * 1024 * DFF, DFF, NREAL, 1024, DFF, e); }
;     grid.sync();
.Lgbx_top_2:
	v_mov_b32_e32 v3, 1
	global_atomic_add v3, v1, v3, s[4:5] sc0
	s_waitcnt vmcnt(0)
	v_and_b32_e32 v3, 0xffff, v3
	s_nop 0
	v_readfirstlane_b32 s1, v3
	s_nop 3
	s_add_i32 s0, s7, -1
	s_cmp_lg_u32 s1, s0
	s_cbranch_scc1 .Lgbx_pp_2
	s_sub_i32 s1, 0x10000, s7
	v_mov_b32_e32 v3, s1
	global_atomic_add v1, v3, s[4:5]
.Lgbx_pp_2:
	buffer_inv sc1
.Lgbx_poll_2:
	global_load_dword v3, v1, s[4:5] sc1
	s_waitcnt vmcnt(0)
	v_and_b32_e32 v3, 0xffff0000, v3
	v_cmp_ne_u32_e32 vcc, v3, v0
	s_cbranch_vccnz .Lgbx_sw_2
	s_sleep 1
	s_branch .Lgbx_poll_2

; __global__ void __launch_bounds__(512) mega(Params P) {
;     ...
;   for (int l = 0; l < 2; ++l) {
;     if (l > 0) { norm_phase(H, P.attn_norm + l * DM, HN); grid.sync(); }
;     { EpiIn e; e.cqkv = CQKV; e.ka = (bf16_t*)(ws + WS_KA); e.qd = (bf16_t*)(ws + WS_QD); e.kd = (bf16_t*)(ws + WS_KD); e.vtd = (bf16_t*)(ws + WS_VTD);
;       e.qs = (bf16_t*)(ws + WS_QS); e.ks = (bf16_t*)(ws + WS_KS); e.vts = (bf16_t*)(ws + WS_VTS); e.rope = rope;
;       if (EN & 2) gemm_phase(HN, DM, (const bf16_t*)(ws + WS_WIN) + (size_t)l * N_IN * 1024, 1024, NREAL, N_IN, 1024, e); }
;     grid.sync();
;     { EpiUp e; e.qa = (bf16_t*)(ws + WS_QA); e.ka = (bf16_t*)(ws + WS_KA); e.vta = (bf16_t*)(ws + WS_VTA); e.rope = rope; e.brow = 0; e.rs_direct = 0.f; e.use_direct = 0;
;       if (EN & 4) up_phase(CQKV, (const bf16_t*)(ws + WS_WQB) + (size_t)l * 768 * 256, (const bf16_t*)(ws + WS_WKVB) + (size_t)l * 768 * 256, e); }
;     grid.sync();
;     attn_phase(P, l);
;     grid.sync();
;     if (l == 0) { EpiResid0 e; e.H = H; e.xsrc = P.x; e.msrc = P.meta; gemm_phase(HN, DM, (const bf16_t*)(ws + WS_WOUT), 1024, NREAL, 1024, 1024, e); }
;     else { EpiResid e; e.H = H; gemm_phase(HN, DM, (const bf16_t*)(ws + WS_WOUT) + (size_t)l * 1024 * 1024, 1024, NREAL, 1024, 1024, e); }
;     grid.sync();
;     norm_phase(H, P.ffn_norm + l * DM, HN);
;     grid.sync();
;     if (EN & 128) { EpiGU e; e.act = (bf16_t*)(ws + WS_ACT); gemm_phase(HN, DM, (const bf16_t*)(ws + WS_WGU) + (size_t)l * N_GU * 1024, 1024, NREAL, N_GU, 1024, e); }
;     grid.sync();
;     if (EN & 256) { EpiResid e; e.H = H; gemm_phase((const bf16_t*)(ws + WS_ACT), DFF, (const bf16_t*)(ws + WS_WDN) + (size_t)l * 1024 * DFF, DFF, NREAL, 1024, DFF, e); }
;     grid.sync();
.Lgbx_top_3:
	v_mov_b32_e32 v3, 1
	global_atomic_add v3, v1, v3, s[4:5] sc0
	s_waitcnt vmcnt(0)
	v_and_b32_e32 v3, 0xffff, v3
	s_nop 0
	v_readfirstlane_b32 s1, v3
	s_nop 3
	s_add_i32 s0, s7, -1
	s_cmp_lg_u32 s1, s0
	s_cbranch_scc1 .Lgbx_pp_3
	s_sub_i32 s1, 0x10000, s7
	v_mov_b32_e32 v3, s1
	global_atomic_add v1, v3, s[4:5]
.Lgbx_pp_3:
	buffer_inv sc1
.Lgbx_poll_3:
	global_load_dword v3, v1, s[4:5] sc1
	s_waitcnt vmcnt(0)
	v_and_b32_e32 v3, 0xffff0000, v3
	v_cmp_ne_u32_e32 vcc, v3, v0
	s_cbranch_vccnz .Lgbx_sw_3
	s_sleep 1
	s_branch .Lgbx_poll_3

; __global__ void __launch_bounds__(512) mega(Params P) {
;     ...
;   for (int l = 0; l < 2; ++l) {
;     if (l > 0) { norm_phase(H, P.attn_norm + l * DM, HN); grid.sync(); }
;     { EpiIn e; e.cqkv = CQKV; e.ka = (bf16_t*)(ws + WS_KA); e.qd = (bf16_t*)(ws + WS_QD); e.kd = (bf16_t*)(ws + WS_KD); e.vtd = (bf16_t*)(ws + WS_VTD);
;       e.qs = (bf16_t*)(ws + WS_QS); e.ks = (bf16_t*)(ws + WS_KS); e.vts = (bf16_t*)(ws + WS_VTS); e.rope = rope;
;       if (EN & 2) gemm_phase(HN, DM, (const bf16_t*)(ws + WS_WIN) + (size_t)l * N_IN * 1024, 1024, NREAL, N_IN, 1024, e); }
;     grid.sync();
;     { EpiUp e; e.qa = (bf16_t*)(ws + WS_QA); e.ka = (bf16_t*)(ws + WS_KA); e.vta = (bf16_t*)(ws + WS_VTA); e.rope = rope; e.brow = 0; e.rs_direct = 0.f; e.use_direct = 0;
;       if (EN & 4) up_phase(CQKV, (const bf16_t*)(ws + WS_WQB) + (size_t)l * 768 * 256, (const bf16_t*)(ws + WS_WKVB) + (size_t)l * 768 * 256, e); }
;     grid.sync();
;     attn_phase(P, l);
;     grid.sync();
;     if (l == 0) { EpiResid0 e; e.H = H; e.xsrc = P.x; e.msrc = P.meta; gemm_phase(HN, DM, (const bf16_t*)(ws + WS_WOUT), 1024, NREAL, 1024, 1024, e); }
;     else { EpiResid e; e.H = H; gemm_phase(HN, DM, (const bf16_t*)(ws + WS_WOUT) + (size_t)l * 1024 * 1024, 1024, NREAL, 1024, 1024, e); }
;     grid.sync();
;     norm_phase(H, P.ffn_norm + l * DM, HN);
;     grid.sync();
;     if (EN & 128) { EpiGU e; e.act = (bf16_t*)(ws + WS_ACT); gemm_phase(HN, DM, (const bf16_t*)(ws + WS_WGU) + (size_t)l * N_GU * 1024, 1024, NREAL, N_GU, 1024, e); }
;     grid.sync();
;     if (EN & 256) { EpiResid e; e.H = H; gemm_phase((const bf16_t*)(ws + WS_ACT), DFF, (const bf16_t*)(ws + WS_WDN) + (size_t)l * 1024 * DFF, DFF, NREAL, 1024, DFF, e); }
;     grid.sync();
.Lgbx_arr_4:
	s_lshl_b32 s1, s1, 2
	s_addk_i32 s1, 0x88
	v_mov_b32_e32 v2, s1
	v_readlane_b32 s98, v255, 20
	s_nop 3
	s_lshl_b32 s99, s98, 16
	v_mov_b32_e32 v0, s99
	s_add_i32 s98, s98, 1
	v_writelane_b32 v255, s98, 20
	v_mov_b32_e32 v3, 1
	global_atomic_add v3, v2, v3, s[6:7] sc0
	s_waitcnt vmcnt(0)
	v_readfirstlane_b32 s1, v3
	s_nop 3
	s_cmp_eq_u32 s96, 0
	s_cbranch_scc1 .Lgbx_cn_4
	s_and_b32 s1, s1, 0xffff
	s_add_i32 s0, s8, -1
	s_cmp_lg_u32 s1, s0
	s_cbranch_scc1 .Lgbx_pp_4
	s_sub_i32 s1, 0x10000, s8
	v_mov_b32_e32 v3, s1
	global_atomic_add v3, v2, v3, s[6:7] sc0
	s_waitcnt vmcnt(0)
	s_branch .Lgbx_top_4

; __global__ void __launch_bounds__(512) mega(Params P) {
;     ...
;   for (int l = 0; l < 2; ++l) {
;     if (l > 0) { norm_phase(H, P.attn_norm + l * DM, HN); grid.sync(); }
;     { EpiIn e; e.cqkv = CQKV; e.ka = (bf16_t*)(ws + WS_KA); e.qd = (bf16_t*)(ws + WS_QD); e.kd = (bf16_t*)(ws + WS_KD); e.vtd = (bf16_t*)(ws + WS_VTD);
;       e.qs = (bf16_t*)(ws + WS_QS); e.ks = (bf16_t*)(ws + WS_KS); e.vts = (bf16_t*)(ws + WS_VTS); e.rope = rope;
;       if (EN & 2) gemm_phase(HN, DM, (const bf16_t*)(ws + WS_WIN) + (size_t)l * N_IN * 1024, 1024, NREAL, N_IN, 1024, e); }
;     grid.sync();
;     { EpiUp e; e.qa = (bf16_t*)(ws + WS_QA); e.ka = (bf16_t*)(ws + WS_KA); e.vta = (bf16_t*)(ws + WS_VTA); e.rope = rope; e.brow = 0; e.rs_direct = 0.f; e.use_direct = 0;
;       if (EN & 4) up_phase(CQKV, (const bf16_t*)(ws + WS_WQB) + (size_t)l * 768 * 256, (const bf16_t*)(ws + WS_WKVB) + (size_t)l * 768 * 256, e); }
;     grid.sync();
;     attn_phase(P, l);
;     grid.sync();
;     if (l == 0) { EpiResid0 e; e.H = H; e.xsrc = P.x; e.msrc = P.meta; gemm_phase(HN, DM, (const bf16_t*)(ws + WS_WOUT), 1024, NREAL, 1024, 1024, e); }
;     else { EpiResid e; e.H = H; gemm_phase(HN, DM, (const bf16_t*)(ws + WS_WOUT) + (size_t)l * 1024 * 1024, 1024, NREAL, 1024, 1024, e); }
;     grid.sync();
;     norm_phase(H, P.ffn_norm + l * DM, HN);
;     grid.sync();
;     if (EN & 128) { EpiGU e; e.act = (bf16_t*)(ws + WS_ACT); gemm_phase(HN, DM, (const bf16_t*)(ws + WS_WGU) + (size_t)l * N_GU * 1024, 1024, NREAL, N_GU, 1024, e); }
;     grid.sync();
;     if (EN & 256) { EpiResid e; e.H = H; gemm_phase((const bf16_t*)(ws + WS_ACT), DFF, (const bf16_t*)(ws + WS_WDN) + (size_t)l * 1024 * DFF, DFF, NREAL, 1024, DFF, e); }
;     grid.sync();
.Lgbx_top_4:
	v_mov_b32_e32 v3, 1
	global_atomic_add v3, v1, v3, s[6:7] sc0
	s_waitcnt vmcnt(0)
	v_and_b32_e32 v3, 0xffff, v3
	s_nop 0
	v_readfirstlane_b32 s1, v3
	s_nop 3
	s_add_i32 s0, s9, -1
	s_cmp_lg_u32 s1, s0
	s_cbranch_scc1 .Lgbx_pp_4
	s_sub_i32 s1, 0x10000, s9
	v_mov_b32_e32 v3, s1
	global_atomic_add v1, v3, s[6:7]
.Lgbx_pp_4:
	buffer_inv sc1
.Lgbx_poll_4:
	global_load_dword v3, v1, s[6:7] sc1
	s_waitcnt vmcnt(0)
	v_and_b32_e32 v3, 0xffff0000, v3
	v_cmp_ne_u32_e32 vcc, v3, v0
	s_cbranch_vccnz .Lgbx_sw_4
	s_sleep 1
	s_branch .Lgbx_poll_4

; __global__ void __launch_bounds__(512) mega(Params P) {
;     ...
;   for (int l = 0; l < 2; ++l) {
;     if (l > 0) { norm_phase(H, P.attn_norm + l * DM, HN); grid.sync(); }
;     { EpiIn e; e.cqkv = CQKV; e.ka = (bf16_t*)(ws + WS_KA); e.qd = (bf16_t*)(ws + WS_QD); e.kd = (bf16_t*)(ws + WS_KD); e.vtd = (bf16_t*)(ws + WS_VTD);
;       e.qs = (bf16_t*)(ws + WS_QS); e.ks = (bf16_t*)(ws + WS_KS); e.vts = (bf16_t*)(ws + WS_VTS); e.rope = rope;
;       if (EN & 2) gemm_phase(HN, DM, (const bf16_t*)(ws + WS_WIN) + (size_t)l * N_IN * 1024, 1024, NREAL, N_IN, 1024, e); }
;     grid.sync();
;     { EpiUp e; e.qa = (bf16_t*)(ws + WS_QA); e.ka = (bf16_t*)(ws + WS_KA); e.vta = (bf16_t*)(ws + WS_VTA); e.rope = rope; e.brow = 0; e.rs_direct = 0.f; e.use_direct = 0;
;       if (EN & 4) up_phase(CQKV, (const bf16_t*)(ws + WS_WQB) + (size_t)l * 768 * 256, (const bf16_t*)(ws + WS_WKVB) + (size_t)l * 768 * 256, e); }
;     grid.sync();
;     attn_phase(P, l);
;     grid.sync();
;     if (l == 0) { EpiResid0 e; e.H = H; e.xsrc = P.x; e.msrc = P.meta; gemm_phase(HN, DM, (const bf16_t*)(ws + WS_WOUT), 1024, NREAL, 1024, 1024, e); }
;     else { EpiResid e; e.H = H; gemm_phase(HN, DM, (const bf16_t*)(ws + WS_WOUT) + (size_t)l * 1024 * 1024, 1024, NREAL, 1024, 1024, e); }
;     grid.sync();
;     norm_phase(H, P.ffn_norm + l * DM, HN);
;     grid.sync();
;     if (EN & 128) { EpiGU e; e.act = (bf16_t*)(ws + WS_ACT); gemm_phase(HN, DM, (const bf16_t*)(ws + WS_WGU) + (size_t)l * N_GU * 1024, 1024, NREAL, N_GU, 1024, e); }
;     grid.sync();
;     if (EN & 256) { EpiResid e; e.H = H; gemm_phase((const bf16_t*)(ws + WS_ACT), DFF, (const bf16_t*)(ws + WS_WDN) + (size_t)l * 1024 * DFF, DFF, NREAL, 1024, DFF, e); }
;     grid.sync();
.Lgbx_top_5:
	v_mov_b32_e32 v3, 1
	global_atomic_add v3, v1, v3, s[6:7] sc0
	s_waitcnt vmcnt(0)
	v_and_b32_e32 v3, 0xffff, v3
	s_nop 0
	v_readfirstlane_b32 s1, v3
	s_nop 3
	s_add_i32 s0, s9, -1
	s_cmp_lg_u32 s1, s0
	s_cbranch_scc1 .Lgbx_pp_5
	s_sub_i32 s1, 0x10000, s9
	v_mov_b32_e32 v3, s1
	global_atomic_add v1, v3, s[6:7]
.Lgbx_pp_5:
	buffer_inv sc1
.Lgbx_poll_5:
	global_load_dword v3, v1, s[6:7] sc1
	s_waitcnt vmcnt(0)
	v_and_b32_e32 v3, 0xffff0000, v3
	v_cmp_ne_u32_e32 vcc, v3, v0
	s_cbranch_vccnz .Lgbx_sw_5
	s_sleep 1
	s_branch .Lgbx_poll_5

; __global__ void __launch_bounds__(512) mega(Params P) {
;     ...
;   for (int l = 0; l < 2; ++l) {
;     if (l > 0) { norm_phase(H, P.attn_norm + l * DM, HN); grid.sync(); }
;     { EpiIn e; e.cqkv = CQKV; e.ka = (bf16_t*)(ws + WS_KA); e.qd = (bf16_t*)(ws + WS_QD); e.kd = (bf16_t*)(ws + WS_KD); e.vtd = (bf16_t*)(ws + WS_VTD);
;       e.qs = (bf16_t*)(ws + WS_QS); e.ks = (bf16_t*)(ws + WS_KS); e.vts = (bf16_t*)(ws + WS_VTS); e.rope = rope;
;       if (EN & 2) gemm_phase(HN, DM, (const bf16_t*)(ws + WS_WIN) + (size_t)l * N_IN * 1024, 1024, NREAL, N_IN, 1024, e); }
;     grid.sync();
;     { EpiUp e; e.qa = (bf16_t*)(ws + WS_QA); e.ka = (bf16_t*)(ws + WS_KA); e.vta = (bf16_t*)(ws + WS_VTA); e.rope = rope; e.brow = 0; e.rs_direct = 0.f; e.use_direct = 0;
;       if (EN & 4) up_phase(CQKV, (const bf16_t*)(ws + WS_WQB) + (size_t)l * 768 * 256, (const bf16_t*)(ws + WS_WKVB) + (size_t)l * 768 * 256, e); }
;     grid.sync();
;     attn_phase(P, l);
;     grid.sync();
;     if (l == 0) { EpiResid0 e; e.H = H; e.xsrc = P.x; e.msrc = P.meta; gemm_phase(HN, DM, (const bf16_t*)(ws + WS_WOUT), 1024, NREAL, 1024, 1024, e); }
;     else { EpiResid e; e.H = H; gemm_phase(HN, DM, (const bf16_t*)(ws + WS_WOUT) + (size_t)l * 1024 * 1024, 1024, NREAL, 1024, 1024, e); }
;     grid.sync();
;     norm_phase(H, P.ffn_norm + l * DM, HN);
;     grid.sync();
;     if (EN & 128) { EpiGU e; e.act = (bf16_t*)(ws + WS_ACT); gemm_phase(HN, DM, (const bf16_t*)(ws + WS_WGU) + (size_t)l * N_GU * 1024, 1024, NREAL, N_GU, 1024, e); }
;     grid.sync();
;     if (EN & 256) { EpiResid e; e.H = H; gemm_phase((const bf16_t*)(ws + WS_ACT), DFF, (const bf16_t*)(ws + WS_WDN) + (size_t)l * 1024 * DFF, DFF, NREAL, 1024, DFF, e); }
;     grid.sync();
.Lgbx_top_6:
	v_mov_b32_e32 v3, 1
	global_atomic_add v3, v1, v3, s[6:7] sc0
	s_waitcnt vmcnt(0)
	v_and_b32_e32 v3, 0xffff, v3
	s_nop 0
	v_readfirstlane_b32 s1, v3
	s_nop 3
	s_add_i32 s0, s9, -1
	s_cmp_lg_u32 s1, s0
	s_cbranch_scc1 .Lgbx_pp_6
	s_sub_i32 s1, 0x10000, s9
	v_mov_b32_e32 v3, s1
	global_atomic_add v1, v3, s[6:7]
.Lgbx_pp_6:
	buffer_inv sc1
.Lgbx_poll_6:
	global_load_dword v3, v1, s[6:7] sc1
	s_waitcnt vmcnt(0)
	v_and_b32_e32 v3, 0xffff0000, v3
	v_cmp_ne_u32_e32 vcc, v3, v0
	s_cbranch_vccnz .Lgbx_sw_6
	s_sleep 1
	s_branch .Lgbx_poll_6

; __global__ void __launch_bounds__(512) mega(Params P) {
;     ...
;   for (int l = 0; l < 2; ++l) {
;     if (l > 0) { norm_phase(H, P.attn_norm + l * DM, HN); grid.sync(); }
;     { EpiIn e; e.cqkv = CQKV; e.ka = (bf16_t*)(ws + WS_KA); e.qd = (bf16_t*)(ws + WS_QD); e.kd = (bf16_t*)(ws + WS_KD); e.vtd = (bf16_t*)(ws + WS_VTD);
;       e.qs = (bf16_t*)(ws + WS_QS); e.ks = (bf16_t*)(ws + WS_KS); e.vts = (bf16_t*)(ws + WS_VTS); e.rope = rope;
;       if (EN & 2) gemm_phase(HN, DM, (const bf16_t*)(ws + WS_WIN) + (size_t)l * N_IN * 1024, 1024, NREAL, N_IN, 1024, e); }
;     grid.sync();
;     { EpiUp e; e.qa = (bf16_t*)(ws + WS_QA); e.ka = (bf16_t*)(ws + WS_KA); e.vta = (bf16_t*)(ws + WS_VTA); e.rope = rope; e.brow = 0; e.rs_direct = 0.f; e.use_direct = 0;
;       if (EN & 4) up_phase(CQKV, (const bf16_t*)(ws + WS_WQB) + (size_t)l * 768 * 256, (const bf16_t*)(ws + WS_WKVB) + (size_t)l * 768 * 256, e); }
;     grid.sync();
;     attn_phase(P, l);
;     grid.sync();
;     if (l == 0) { EpiResid0 e; e.H = H; e.xsrc = P.x; e.msrc = P.meta; gemm_phase(HN, DM, (const bf16_t*)(ws + WS_WOUT), 1024, NREAL, 1024, 1024, e); }
;     else { EpiResid e; e.H = H; gemm_phase(HN, DM, (const bf16_t*)(ws + WS_WOUT) + (size_t)l * 1024 * 1024, 1024, NREAL, 1024, 1024, e); }
;     grid.sync();
;     norm_phase(H, P.ffn_norm + l * DM, HN);
;     grid.sync();
;     if (EN & 128) { EpiGU e; e.act = (bf16_t*)(ws + WS_ACT); gemm_phase(HN, DM, (const bf16_t*)(ws + WS_WGU) + (size_t)l * N_GU * 1024, 1024, NREAL, N_GU, 1024, e); }
;     grid.sync();
;     if (EN & 256) { EpiResid e; e.H = H; gemm_phase((const bf16_t*)(ws + WS_ACT), DFF, (const bf16_t*)(ws + WS_WDN) + (size_t)l * 1024 * DFF, DFF, NREAL, 1024, DFF, e); }
;     grid.sync();
.Lgbx_top_7:
	v_mov_b32_e32 v3, 1
	global_atomic_add v3, v1, v3, s[4:5] sc0
	s_waitcnt vmcnt(0)
	v_and_b32_e32 v3, 0xffff, v3
	s_nop 0
	v_readfirstlane_b32 s1, v3
	s_nop 3
	s_add_i32 s0, s7, -1
	s_cmp_lg_u32 s1, s0
	s_cbranch_scc1 .Lgbx_pp_7
	s_sub_i32 s1, 0x10000, s7
	v_mov_b32_e32 v3, s1
	global_atomic_add v1, v3, s[4:5]
.Lgbx_pp_7:
	buffer_inv sc1
.Lgbx_poll_7:
	global_load_dword v3, v1, s[4:5] sc1
	s_waitcnt vmcnt(0)
	v_and_b32_e32 v3, 0xffff0000, v3
	v_cmp_ne_u32_e32 vcc, v3, v0
	s_cbranch_vccnz .Lgbx_sw_7
	s_sleep 1
	s_branch .Lgbx_poll_7
